# grid barrier: everyone polls the top-level arrival counter (>= target) instead of a separate generation word, removing one atomic hop; last leader no longer bumps the generation word
# baseline (speedup 1.0000x reference)
.LBB0_1934:
	s_or_b64 exec, exec, s[2:3]
	v_cvt_f32_u32_e32 v5, v3
	s_waitcnt vmcnt(0)
	v_readfirstlane_b32 s2, v4
	v_sub_u32_e32 v4, 0, v3
	v_rcp_iflag_f32_e32 v5, v5
	v_add_u32_e32 v6, s2, v0
	v_mul_f32_e32 v5, 0x4f7ffffe, v5
	v_cvt_u32_f32_e32 v5, v5
	v_mul_lo_u32 v0, v4, v5
	v_mul_hi_u32 v0, v5, v0
	v_add_u32_e32 v0, v5, v0
	v_mul_hi_u32 v0, v6, v0
	v_mul_lo_u32 v4, v0, v3
	v_sub_u32_e32 v4, v6, v4
	v_add_u32_e32 v5, 1, v0
	v_cmp_ge_u32_e32 vcc, v4, v3
	s_nop 1
	v_cndmask_b32_e32 v0, v0, v5, vcc
	v_sub_u32_e32 v5, v4, v3
	v_cndmask_b32_e32 v4, v4, v5, vcc
	v_add_u32_e32 v5, 1, v0
	v_cmp_ge_u32_e32 vcc, v4, v3
	v_add_u32_e32 v4, 1, v6
	s_nop 0
	v_cndmask_b32_e32 v0, v0, v5, vcc
	v_mul_lo_u32 v5, v3, v0
	v_add_u32_e32 v3, v5, v3
	v_cmp_ne_u32_e32 vcc, v4, v3
	s_and_saveexec_b64 s[2:3], vcc
	s_xor_b64 s[2:3], exec, s[2:3]
	s_cbranch_execz .LBB0_1948
	v_readlane_b32 s4, v254, 29
	v_readlane_b32 s5, v254, 30
	s_waitcnt lgkmcnt(0)
	v_add_u32_e32 v7, 1, v0
	v_mul_lo_u32 v7, v7, v2
	s_nop 3
	global_load_dword v2, v1, s[4:5] offset:-256 sc1
	s_waitcnt vmcnt(0)
	v_cmp_lt_u32_e32 vcc, v2, v7
	s_and_saveexec_b64 s[4:5], vcc
	s_cbranch_execz .LBB0_1947
	s_mov_b32 s17, 1
	s_mov_b64 s[6:7], 0
	s_branch .LBB0_1938

.LBB0_1940:
	v_readlane_b32 s10, v254, 29
	v_readlane_b32 s11, v254, 30
	s_add_i32 s17, s17, 1
	s_mov_b64 s[12:13], -1
	s_nop 2
	global_load_dword v2, v1, s[10:11] offset:-256 sc1
	s_waitcnt vmcnt(0)
	v_cmp_ge_u32_e32 vcc, v2, v7
	s_orn2_b64 s[10:11], vcc, exec
	s_branch .LBB0_1937

.LBB0_1951:
	s_or_b64 exec, exec, s[4:5]
	s_waitcnt vmcnt(0)
	v_readfirstlane_b32 s2, v3
	v_sub_u32_e32 v4, 0, v2
	s_mov_b64 s[4:5], 0
	v_add_u32_e32 v3, s2, v0
	v_cvt_f32_u32_e32 v0, v2
	v_readlane_b32 s2, v254, 29
	v_readlane_b32 s3, v254, 30
	v_rcp_iflag_f32_e32 v0, v0
	s_nop 0
	v_mul_f32_e32 v0, 0x4f7ffffe, v0
	v_cvt_u32_f32_e32 v0, v0
	v_mul_lo_u32 v4, v4, v0
	v_mul_hi_u32 v4, v0, v4
	v_add_u32_e32 v0, v0, v4
	v_mul_hi_u32 v0, v3, v0
	v_mul_lo_u32 v4, v0, v2
	v_sub_u32_e32 v4, v3, v4
	v_cmp_ge_u32_e32 vcc, v4, v2
	v_add_u32_e32 v5, 1, v0
	v_add_u32_e32 v3, 1, v3
	v_cndmask_b32_e32 v0, v0, v5, vcc
	v_sub_u32_e32 v5, v4, v2
	v_cndmask_b32_e32 v4, v4, v5, vcc
	v_cmp_ge_u32_e32 vcc, v4, v2
	v_add_u32_e32 v4, 1, v0
	s_nop 0
	v_cndmask_b32_e32 v0, v0, v4, vcc
	v_mul_lo_u32 v4, v2, v0
	v_add_u32_e32 v2, v4, v2
	v_mov_b32_e32 v7, v2
	v_cmp_ne_u32_e32 vcc, v3, v2
	v_mov_b64_e32 v[2:3], s[2:3]
	s_and_saveexec_b64 s[2:3], vcc
	s_cbranch_execz .LBB0_1963
	v_readlane_b32 s4, v254, 29
	v_readlane_b32 s5, v254, 30
	s_mov_b64 s[6:7], 0
	s_nop 3
	global_load_dword v2, v1, s[4:5] offset:-256 sc1
	s_waitcnt vmcnt(0)
	v_cmp_lt_u32_e32 vcc, v2, v7
	s_and_saveexec_b64 s[4:5], vcc
	s_cbranch_execz .LBB0_1962
	s_mov_b32 s17, 1
	s_branch .LBB0_1955
